# stack27: stack26 + cmp unit prologue de-serialisation: K/V tile-0 requests issued with the query rows ahead of the LDS clear loop
# speedup vs baseline: 1.0005x; 1.0005x over previous
.LBB0_1301:
	s_ashr_i32 s0, s24, 2
	s_lshl_b32 s30, s33, 6
	s_lshl_b32 s1, s24, 2
	v_add_u32_e32 v18, s30, v177
	v_and_or_b32 v232, s1, 12, v178
	s_ashr_i32 s1, s0, 31
	s_lshl_b64 s[0:1], s[0:1], 13
	v_ashrrev_i32_e32 v19, 31, v18
	v_lshl_add_u64 v[154:155], s[0:1], 0, v[18:19]
	v_mov_b64_e32 v[2:3], s[82:83]
	v_mad_u64_u32 v[158:159], s[0:1], v154, s21, v[2:3]
	v_mad_i32_i24 v159, v155, s21, v159
	v_lshlrev_b32_e32 v146, 7, v232
	v_lshl_add_u64 v[2:3], v[158:159], 0, v[146:147]
	v_lshl_add_u64 v[2:3], v[138:139], 1, v[2:3]
	s_mov_b64 s[0:1], 0x1800
	v_lshl_add_u64 v[4:5], v[2:3], 0, s[0:1]
	v_add_co_u32_e32 v2, vcc, 0x1000, v2
	v_lshlrev_b32_e32 v156, 6, v232
	s_nop 0
	v_addc_co_u32_e32 v3, vcc, 0, v3, vcc
	global_load_dwordx4 v[86:89], v[4:5], off offset:32
	global_load_dwordx4 v[90:93], v[4:5], off offset:64
	global_load_dwordx4 v[94:97], v[2:3], off offset:2048
	global_load_dwordx4 v[98:101], v[4:5], off offset:96
	v_mul_u32_u24_e32 v241, 3, v232
	v_lshlrev_b32_e32 v242, 1, v241
	v_mov_b32_e32 v243, 0
	v_lshl_add_u64 v[242:243], v[158:159], 0, v[242:243]
	v_add_co_u32_e32 v242, vcc, 0x3000, v242
	s_nop 1
	v_addc_co_u32_e32 v243, vcc, 0, v243, vcc
	global_load_ushort v241, v[242:243], off offset:3104
	s_ashr_i32 s25, s24, 31
	s_lshl_b64 s[98:99], s[24:25], 16
	s_add_u32 s98, s20, s98
	s_addc_u32 s99, s19, s99
	v_lshl_add_u64 v[2:3], s[98:99], 0, v[144:145]
	v_lshlrev_b32_e32 v114, 1, v148
	v_mov_b32_e32 v115, v147
	s_add_u32 s100, s98, 0x880000
	v_lshl_add_u64 v[2:3], v[2:3], 0, v[114:115]
	s_addc_u32 s101, s99, 0
	global_load_dwordx4 v[50:53], v[2:3], off
	v_lshl_add_u64 v[2:3], s[100:101], 0, v[144:145]
	v_lshl_add_u64 v[2:3], v[2:3], 0, v[114:115]
	global_load_dwordx4 v[54:57], v[2:3], off
	v_lshl_add_u64 v[160:161], s[98:99], 0, v[114:115]
	s_mov_b64 s[0:1], 0
	v_mov_b32_e32 v2, v172
	v_mov_b32_e32 v3, v202
.LBB0_1302:
	v_add_u32_e32 v2, 64, v2
	s_movk_i32 s2, 0x3bf
	v_cmp_lt_u32_e32 vcc, s2, v2
	ds_write_b32 v3, v147
	s_or_b64 s[0:1], vcc, s[0:1]
	v_add_u32_e32 v3, 0x100, v3
	s_andn2_b64 exec, exec, s[0:1]
	s_cbranch_execnz .LBB0_1302
	s_or_b64 exec, exec, s[0:1]
	s_and_saveexec_b64 s[0:1], s[40:41]
	ds_write_b32 v206, v147 offset:36864
	s_or_b64 exec, exec, s[0:1]
	s_mov_b64 s[0:1], s[100:101]
	s_add_i32 s2, s30, s15
	s_sub_i32 s3, s2, 31
	v_subrev_u32_e32 v2, 31, v18
	s_ashr_i32 s8, s33, 4
	s_ashr_i32 s3, s3, 4
	v_ashrrev_i32_e32 v19, 4, v2
	v_cmp_lt_i32_e32 vcc, 30, v18
	s_cmp_gt_i32 s2, 30
	v_mov_b32_e32 v17, 0
	v_cndmask_b32_e32 v233, -1, v19, vcc
	s_cselect_b32 s9, s3, -1
	s_cmp_gt_i32 s8, -1
	v_mov_b32_e32 v16, v17
	v_mov_b32_e32 v15, v17
	v_mov_b32_e32 v14, v17
	v_mov_b32_e32 v13, v17
	v_mov_b32_e32 v12, v17
	v_mov_b32_e32 v11, v17
	v_mov_b32_e32 v10, v17
	v_mov_b32_e32 v9, v17
	v_mov_b32_e32 v8, v17
	v_mov_b32_e32 v7, v17
	v_mov_b32_e32 v6, v17
	v_mov_b32_e32 v5, v17
	v_mov_b32_e32 v4, v17
	v_mov_b32_e32 v3, v17
	v_mov_b32_e32 v2, v17
	v_subrev_u32_e32 v234, 32, v233
	s_cselect_b64 s[2:3], -1, 0
	s_cmp_lt_i32 s8, 0
	v_mov_b32_e32 v115, v17
	s_waitcnt vmcnt(1)
	v_mov_b64_e32 v[104:105], v[52:53]
	v_mov_b64_e32 v[102:103], v[50:51]
	ds_write_b128 v180, v[50:53]
	s_waitcnt lgkmcnt(0)
	s_barrier
	s_cbranch_scc1 .LBB0_1320
	v_mov_b32_e32 v115, 0
	v_mov_b64_e32 v[104:105], v[52:53]
	s_add_i32 s10, s8, 1
	s_mov_b32 s11, 0
	s_mov_b32 s12, 63
	v_mov_b32_e32 v116, 0
	v_mov_b64_e32 v[102:103], v[50:51]
	v_mov_b32_e32 v2, 0
	v_mov_b32_e32 v3, v115
	v_mov_b32_e32 v4, v115
	v_mov_b32_e32 v5, v115
	v_mov_b32_e32 v6, v115
	v_mov_b32_e32 v7, v115
	v_mov_b32_e32 v8, v115
	v_mov_b32_e32 v9, v115
	v_mov_b32_e32 v10, v115
	v_mov_b32_e32 v11, v115
	v_mov_b32_e32 v12, v115
	v_mov_b32_e32 v13, v115
	v_mov_b32_e32 v14, v115
	v_mov_b32_e32 v15, v115
	v_mov_b32_e32 v16, v115
	v_mov_b32_e32 v17, v115
	s_branch .LBB0_1308
